# phase 2 tile order: per-XCD 2-D blocking (8 row panels x 8 column tiles per round, 25th column as a half round on one block per CU pair), phase 13 pairs share the weight tile
# speedup vs baseline: 1.0377x; 1.0052x over previous
.LBB0_120:
	s_or_b64 exec, exec, s[0:1]
	s_and_b32 s0, s92, 7
	s_cmp_eq_u32 s0, 0
	s_cselect_b64 s[4:5], -1, 0
	s_cmp_lg_u32 s0, 0
	s_mov_b32 s3, s2
	s_mov_b32 s99, 0
	s_waitcnt lgkmcnt(0)
	s_barrier
	s_cbranch_scc0 .LBB0_122
	s_add_u32 s44, s26, 0x9800000
	s_addc_u32 s45, s27, 0
	s_cmpk_gt_i32 s3, 0x18ff
	s_cbranch_scc0 .LBB0_123
	s_branch .LBB0_141
.LBB0_122:
	s_and_b32 s0, s2, 7
	s_lshr_b32 s1, s92, 3
	s_cmp_lg_u32 s1, 64
	s_cbranch_scc1 .Lt2d_plain
	s_mov_b32 s99, 1
	s_mov_b32 s98, 0
	s_mul_i32 s0, s0, 0x320
	s_lshr_b32 s1, s2, 3
	s_mul_i32 vcc_lo, s1, 25
	s_add_u32 vcc_lo, vcc_lo, s0
	s_add_u32 vcc_lo, vcc_lo, 24
	s_cmp_lt_u32 s1, 32
	s_cselect_b32 s101, vcc_lo, 0x7fff
	s_lshr_b32 vcc_lo, s1, 3
	s_mul_i32 vcc_lo, vcc_lo, 25
	s_and_b32 s1, s1, 7
	s_add_u32 s100, s0, vcc_lo
	s_add_u32 s100, s100, s1
	s_mov_b32 s3, s100
	s_branch .Lt2d_set
.Lt2d_plain:
	s_mul_i32 s0, s1, s0
	s_lshr_b32 s1, s2, 3
	s_add_i32 s3, s0, s1
.Lt2d_set:
	s_add_u32 s44, s26, 0x9800000
	s_addc_u32 s45, s27, 0
	s_cmpk_gt_i32 s3, 0x18ff
	s_cbranch_scc1 .LBB0_141

.LBB0_133:
	s_cmp_eq_u32 s99, 0
	s_cbranch_scc1 .Lt2d_adv0
	s_add_u32 s98, s98, 1
	s_cmp_lt_u32 s98, 12
	s_cbranch_scc0 .Lt2d_tail
	s_and_b32 s3, s98, 3
	s_mul_i32 s3, s3, 0xc8
	s_lshr_b32 vcc_lo, s98, 2
	s_lshl_b32 vcc_lo, vcc_lo, 3
	s_add_u32 s3, s3, vcc_lo
	s_add_u32 s3, s3, s100
	s_branch .Lt2d_advd
.Lt2d_tail:
	s_cmp_eq_u32 s98, 12
	s_cselect_b32 s3, s101, 0x7fff
	s_branch .Lt2d_advd

.Lt2d_advd:
	s_cmpk_gt_i32 s3, 0x18ff
	s_cselect_b64 s[12:13], -1, 0
	s_cmpk_lt_i32 s3, 0x1900
	s_mov_b32 s16, s10
	s_mov_b32 s17, s19
	s_cbranch_scc1 .LBB0_136
	s_cmpk_gt_i32 s10, 0xbff
	s_mov_b64 s[14:15], -1
	s_cbranch_scc1 .LBB0_137

.LBB0_691:
	s_and_b32 s4, s2, 7
	s_lshr_b32 s5, s92, 3
	s_mul_i32 s4, s5, s4
	s_lshr_b32 vcc_lo, s2, 3
	s_cmp_lg_u32 s5, 64
	s_cbranch_scc1 .Ltn3_done
	s_cmp_lt_u32 vcc_lo, 30
	s_cbranch_scc0 .Ltn3_b
	s_cmp_lt_u32 vcc_lo, 10
	s_cbranch_scc1 .Ltn3_done
	s_cmp_lt_u32 vcc_lo, 20
	s_cselect_b32 s5, 10, 20
	s_add_u32 vcc_lo, vcc_lo, s5
	s_branch .Ltn3_done
.Ltn3_b:
	s_cmp_lt_u32 vcc_lo, 32
	s_cbranch_scc0 .Ltn3_c
	s_add_u32 vcc_lo, vcc_lo, 30
	s_branch .Ltn3_done
.Ltn3_c:
	s_cmp_lt_u32 vcc_lo, 62
	s_cbranch_scc0 .Ltn3_done
	s_sub_u32 vcc_lo, vcc_lo, 32
	s_cmp_lt_u32 vcc_lo, 10
	s_cselect_b32 s5, 10, 20
	s_cmp_lt_u32 vcc_lo, 20
	s_cselect_b32 s5, s5, 30
	s_add_u32 vcc_lo, vcc_lo, s5
.Ltn3_done:
	s_add_i32 s16, s4, vcc_lo
	s_cmpk_gt_i32 s16, 0x9ff
	s_cbranch_scc1 .LBB0_710
